# group B: DMA issue moved into QK MFMA gaps, first PV MFMA right after barrier
# speedup vs baseline: 1.0168x; 1.0087x over previous
; DI int crow(int i, int hh) { return (i & 3) + 8 * (i >> 2) + 4 * hh; }
; DI void diff_core(unsigned char* smem, const u16* qptr, const u16* kbase, const u16* vtbase, int vld,
;                   int ntb, int ntw, int nvalid, int ks0, const float* lut, int qpos, bool active, bool grpB,
;                   f32x16 (&O)[4], float& l_out) {
;     ...
;     if (lut != nullptr && t >= ntw - 3) {
;       const int base = t * 64 - qpos + 191;
; #pragma unroll
;       for (int kb = 0; kb < 2; ++kb)
; #pragma unroll
;         for (int i = 0; i < 16; ++i) S[kb][i] += lut[base + kb * 32 + crow(i, hh)];
;     }
;     ...
;     for (int t = 0; t <= ntb; ++t) {
;       const bool act_t = active && (t < ntw);
;       { const int tn = t + 2; dma(tn < tlast ? tn : tlast, tn & 3); }
;       if (act_t) softmax(t);
.LBB0_378:
	s_add_i32 s64, s62, 0x101
	s_add_i32 s65, s62, 0x104
	s_min_i32 s65, s65, s58
	s_add_i32 s66, s59, 0x8000
	s_and_b32 s66, s66, 0x18000
	s_add_i32 s85, s6, s66
	s_lshl_b32 s66, s65, 6
	s_ashr_i32 s67, s66, 31
	s_lshl_b64 s[86:87], s[66:67], 11
	s_add_u32 s86, s14, s86
	s_addc_u32 s87, s15, s87
	s_lshl_b64 s[66:67], s[66:67], 1
	s_add_i32 s65, s85, 0x2000
	s_add_u32 s66, s20, s66
	s_addc_u32 s67, s21, s67
	s_add_i32 s88, s85, 0x4000
	s_add_i32 s89, s85, 0x6000
	s_add_i32 s101, s59, 0xffff8000
	s_and_b32 s101, s101, 0x18000
	s_cmp_lt_u32 s64, s16
	s_cselect_b64 s[0:1], -1, 0
	s_cmp_ge_u32 s64, s16
	s_cbranch_scc1 .LBB0_384
	s_add_i32 s100, s59, 0xffff0000
	s_and_b32 s100, s100, 0x18000
	v_add_u32_e32 v248, s100, v188
	ds_read_b128 v[200:203], v248 offset:16384
	ds_read_b128 v[204:207], v248 offset:20480
	ds_read_b128 v[208:211], v248 offset:24576
	ds_read_b128 v[212:215], v248 offset:28672
	v_add_u32_e32 v249, s100, v187
	ds_read_b128 v[216:219], v249 offset:16384
	ds_read_b128 v[220:223], v249 offset:20480
	ds_read_b128 v[224:227], v249 offset:24576
	ds_read_b128 v[228:231], v249 offset:28672
	s_cmp_lt_i32 s64, s17
	s_cbranch_scc1 .LBB0_381
	ds_read2_b32 v[98:99], v96 offset1:1
	ds_read2_b32 v[100:101], v96 offset0:16 offset1:17
	ds_read2_b32 v[102:103], v96 offset0:18 offset1:19
	ds_read2_b32 v[104:105], v96 offset0:24 offset1:25
	ds_read2_b32 v[106:107], v96 offset0:26 offset1:27
	ds_read2_b32 v[108:109], v96 offset0:2 offset1:3
	ds_read2_b32 v[110:111], v96 offset0:8 offset1:9
	ds_read2_b32 v[112:113], v96 offset0:10 offset1:11
	s_waitcnt lgkmcnt(0)
	v_pk_add_f32 v[80:81], v[80:81], v[98:99]
	v_pk_add_f32 v[94:95], v[94:95], v[106:107]
	v_pk_add_f32 v[92:93], v[92:93], v[104:105]
	v_pk_add_f32 v[90:91], v[90:91], v[102:103]
	v_pk_add_f32 v[88:89], v[88:89], v[100:101]
	v_pk_add_f32 v[86:87], v[86:87], v[112:113]
	v_pk_add_f32 v[84:85], v[84:85], v[110:111]
	v_pk_add_f32 v[82:83], v[82:83], v[108:109]
	ds_read2_b32 v[98:99], v96 offset0:32 offset1:33
	ds_read2_b32 v[100:101], v96 offset0:48 offset1:49
	ds_read2_b32 v[102:103], v96 offset0:50 offset1:51
	ds_read2_b32 v[104:105], v96 offset0:56 offset1:57
	ds_read2_b32 v[106:107], v96 offset0:58 offset1:59
	ds_read2_b32 v[108:109], v96 offset0:34 offset1:35
	ds_read2_b32 v[110:111], v96 offset0:40 offset1:41
	ds_read2_b32 v[112:113], v96 offset0:42 offset1:43
	s_waitcnt lgkmcnt(0)
	v_pk_add_f32 v[64:65], v[64:65], v[98:99]
	v_pk_add_f32 v[78:79], v[78:79], v[106:107]
	v_pk_add_f32 v[76:77], v[76:77], v[104:105]
	v_pk_add_f32 v[74:75], v[74:75], v[102:103]
	v_pk_add_f32 v[72:73], v[72:73], v[100:101]
	v_pk_add_f32 v[70:71], v[70:71], v[112:113]
	v_pk_add_f32 v[68:69], v[68:69], v[110:111]
	v_pk_add_f32 v[66:67], v[66:67], v[108:109]

; #define MFMA(a, b, c) __builtin_amdgcn_mfma_f32_32x32x16_bf16((a), (b), (c), 0, 0, 0)
; #define LAS __attribute__((address_space(3)))
; DI void diff_core(unsigned char* smem, const u16* qptr, const u16* kbase, const u16* vtbase, int vld,
;                   int ntb, int ntw, int nvalid, int ks0, const float* lut, int qpos, bool active, bool grpB,
;                   f32x16 (&O)[4], float& l_out) {
;     ...
;   auto pv = [&](int slot) {
;     if (grpB) __builtin_amdgcn_s_setprio(2); else __builtin_amdgcn_s_setprio(1);
;     const LAS unsigned char* b = lds + slot * D_SLOT;
;     bf16x8 va[4], vb[4];
; #pragma unroll
;     for (int tt = 0; tt < 4; ++tt) va[tt] = *reinterpret_cast<const LAS bf16x8*>(b + voff[0] + tt * 32 * 128);
; #pragma unroll
;     for (int tt = 0; tt < 4; ++tt) vb[tt] = *reinterpret_cast<const LAS bf16x8*>(b + voff[1] + tt * 32 * 128);
;     {
;       const bf16x8 pf = __builtin_bit_cast(bf16x8, P[0]);
; #pragma unroll
;       for (int tt = 0; tt < 4; ++tt) O[tt] = MFMA(va[tt], pf, O[tt]);
;     }
; #pragma unroll
;     for (int tt = 0; tt < 4; ++tt) va[tt] = *reinterpret_cast<const LAS bf16x8*>(b + voff[2] + tt * 32 * 128);
;     {
;       const bf16x8 pf = __builtin_bit_cast(bf16x8, P[1]);
; #pragma unroll
;       for (int tt = 0; tt < 4; ++tt) O[tt] = MFMA(vb[tt], pf, O[tt]);
;     }
; #pragma unroll
;     for (int tt = 0; tt < 4; ++tt) vb[tt] = *reinterpret_cast<const LAS bf16x8*>(b + voff[3] + tt * 32 * 128);
;     {
;       const bf16x8 pf = __builtin_bit_cast(bf16x8, P[2]);
; #pragma unroll
;       for (int tt = 0; tt < 4; ++tt) O[tt] = MFMA(va[tt], pf, O[tt]);
;     }
;     {
;       const bf16x8 pf = __builtin_bit_cast(bf16x8, P[3]);
; #pragma unroll
;       for (int tt = 0; tt < 4; ++tt) O[tt] = MFMA(vb[tt], pf, O[tt]);
;     }
;     __builtin_amdgcn_sched_group_barrier(0x100, 8, 0);
;     __builtin_amdgcn_sched_group_barrier(0x008, 4, 0);
;     __builtin_amdgcn_sched_group_barrier(0x100, 4, 0);
;     __builtin_amdgcn_sched_group_barrier(0x008, 4, 0);
;     __builtin_amdgcn_sched_group_barrier(0x100, 4, 0);
;     __builtin_amdgcn_sched_group_barrier(0x008, 8, 0);
;     __builtin_amdgcn_s_setprio(0);
;   };
;     ...
;       asm volatile("s_waitcnt vmcnt(4)" ::: "memory");
;       D_BAR;
;       if (act_t) pv(t & 3);
;       __builtin_amdgcn_sched_barrier(0);
;       if (active && (t + 1) < ntw) qk((t + 1) & 3);
.LBB0_384:
	s_waitcnt vmcnt(4)
	s_barrier
	s_andn2_b64 vcc, exec, s[0:1]
	s_cbranch_vccnz .LBB0_386
	s_setprio 2
	s_waitcnt lgkmcnt(0)
	v_mfma_f32_32x32x16_bf16 v[48:63], v[200:203], v[144:147], v[48:63]
	v_cvt_pk_bf16_f32 v148, v88, v89
	v_add_f32_e32 v250, v83, v250
	v_add_f32_e32 v250, v84, v250
	v_add_u32_e32 v97, s100, v186
	ds_read_b128 v[98:101], v97 offset:16384
	ds_read_b128 v[102:105], v97 offset:20480
	ds_read_b128 v[106:109], v97 offset:24576
	ds_read_b128 v[110:113], v97 offset:28672
	v_mfma_f32_32x32x16_bf16 v[32:47], v[204:207], v[144:147], v[32:47]
	v_cvt_pk_bf16_f32 v149, v90, v91
	v_add_f32_e32 v250, v85, v250
	v_add_f32_e32 v250, v86, v250
	v_add_u32_e32 v126, s100, v184
	ds_read_b128 v[114:117], v126 offset:16384
	ds_read_b128 v[118:121], v126 offset:20480
	ds_read_b128 v[122:125], v126 offset:24576
	ds_read_b128 v[196:199], v126 offset:28672
	v_mfma_f32_32x32x16_bf16 v[16:31], v[208:211], v[144:147], v[16:31]
	v_cvt_pk_bf16_f32 v150, v92, v93
	v_add_f32_e32 v250, v87, v250
	v_add_f32_e32 v250, v88, v250
	v_mfma_f32_32x32x16_bf16 v[0:15], v[212:215], v[144:147], v[0:15]
	v_cvt_pk_bf16_f32 v151, v94, v95
	v_add_f32_e32 v250, v89, v250
	v_add_f32_e32 v250, v90, v250
	v_mfma_f32_32x32x16_bf16 v[48:63], v[216:219], v[148:151], v[48:63]
	v_cvt_pk_bf16_f32 v152, v64, v65
	v_add_f32_e32 v250, v91, v250
	v_add_f32_e32 v250, v92, v250
	v_mfma_f32_32x32x16_bf16 v[32:47], v[220:223], v[148:151], v[32:47]
	v_cvt_pk_bf16_f32 v153, v66, v67
	v_add_f32_e32 v250, v93, v250
	v_add_f32_e32 v250, v94, v250
	v_mfma_f32_32x32x16_bf16 v[16:31], v[224:227], v[148:151], v[16:31]
	v_cvt_pk_bf16_f32 v154, v68, v69
	v_add_f32_e32 v250, v95, v250
	v_add_f32_e32 v250, v64, v250
	v_mfma_f32_32x32x16_bf16 v[0:15], v[228:231], v[148:151], v[0:15]
	v_cvt_pk_bf16_f32 v155, v70, v71
	v_add_f32_e32 v250, v65, v250
	v_add_f32_e32 v250, v66, v250
	v_add_u32_e32 v97, s101, v177
	ds_read_b128 v[200:203], v97
	ds_read_b128 v[204:207], v97 offset:8192
	v_add_u32_e32 v126, s101, v178
	ds_read_b128 v[208:211], v126
	ds_read_b128 v[212:215], v126 offset:8192
	s_waitcnt lgkmcnt(8)
	v_mfma_f32_32x32x16_bf16 v[48:63], v[98:101], v[152:155], v[48:63]
	v_cvt_pk_bf16_f32 v156, v72, v73
	v_add_f32_e32 v250, v67, v250
	v_add_f32_e32 v250, v68, v250
	v_mfma_f32_32x32x16_bf16 v[32:47], v[102:105], v[152:155], v[32:47]
	v_cvt_pk_bf16_f32 v157, v74, v75
	v_add_f32_e32 v250, v69, v250
	v_add_f32_e32 v250, v70, v250
	v_mfma_f32_32x32x16_bf16 v[16:31], v[106:109], v[152:155], v[16:31]
	v_cvt_pk_bf16_f32 v158, v76, v77
	v_add_f32_e32 v250, v71, v250
	v_add_f32_e32 v250, v72, v250
	v_mfma_f32_32x32x16_bf16 v[0:15], v[110:113], v[152:155], v[0:15]
	v_cvt_pk_bf16_f32 v159, v78, v79
	v_add_f32_e32 v250, v73, v250
	v_add_f32_e32 v250, v74, v250
	v_add_u32_e32 v97, s101, v179
	ds_read_b128 v[216:219], v97
	ds_read_b128 v[220:223], v97 offset:8192
	v_add_u32_e32 v126, s101, v180
	ds_read_b128 v[224:227], v126
	ds_read_b128 v[228:231], v126 offset:8192
	s_waitcnt lgkmcnt(8)
	v_mfma_f32_32x32x16_bf16 v[48:63], v[114:117], v[156:159], v[48:63]
	v_add_f32_e32 v250, v75, v250
	v_add_f32_e32 v250, v76, v250
	v_mfma_f32_32x32x16_bf16 v[32:47], v[118:121], v[156:159], v[32:47]
	v_add_f32_e32 v250, v77, v250
	v_add_f32_e32 v250, v78, v250
	v_mfma_f32_32x32x16_bf16 v[16:31], v[122:125], v[156:159], v[16:31]
	v_add_f32_e32 v250, v79, v250
	v_mfma_f32_32x32x16_bf16 v[0:15], v[196:199], v[156:159], v[0:15]
	v_add_f32_e32 v181, v181, v250
	s_setprio 0
.LBB0_386:
	s_add_i32 s0, s62, 0x102
	s_cmp_ge_u32 s0, s16
	s_cbranch_scc1 .LB_dma_only
	s_setprio 2
	s_waitcnt lgkmcnt(0)
	s_mov_b32 m0, s85
	v_mfma_f32_32x32x16_bf16 v[80:95], v[200:203], v[128:131], v[232:247]
	global_load_lds_dwordx4 v162, s[86:87]
	v_mfma_f32_32x32x16_bf16 v[64:79], v[204:207], v[128:131], v[232:247]
	s_mov_b32 m0, s65
	v_mfma_f32_32x32x16_bf16 v[80:95], v[208:211], v[132:135], v[80:95]
	global_load_lds_dwordx4 v170, s[86:87]
	v_mfma_f32_32x32x16_bf16 v[64:79], v[212:215], v[132:135], v[64:79]
	s_mov_b32 m0, s88
	v_mfma_f32_32x32x16_bf16 v[80:95], v[216:219], v[136:139], v[80:95]
	global_load_lds_dwordx4 v166, s[66:67]
	v_mfma_f32_32x32x16_bf16 v[64:79], v[220:223], v[136:139], v[64:79]
	s_mov_b32 m0, s89
	v_mfma_f32_32x32x16_bf16 v[80:95], v[224:227], v[140:143], v[80:95]
	global_load_lds_dwordx4 v168, s[66:67]
	v_mfma_f32_32x32x16_bf16 v[64:79], v[228:231], v[140:143], v[64:79]
	s_setprio 0
	s_branch .LBB0_377
